# gMLP mixing phase: LDS tile rows skewed by 16 B per 16-row block to remove the 16-way bank conflict of the transposing ds_write_b16
# speedup vs baseline: 1.0429x; 1.0060x over previous
; __device__ __forceinline__ float bf_lo(unsigned w) { return __uint_as_float(w << 16); }
; __device__ __forceinline__ void mix_phase(const Args& a, LAS unsigned char* lds, int G, int wv, size_t aa_out = WS_D) {
;     int tid_; asm volatile("v_mbcnt_lo_u32_b32 %0, -1, 0\n\tv_mbcnt_hi_u32_b32 %0, -1, %0" : "=v"(tid_)); tid_ |= (wv << 6); const int tid = tid_, lane = tid & 63, w = __builtin_amdgcn_readfirstlane(tid >> 6);
;     const float* Ws = (const float*)a.in[9]; const float* bs = (const float*)a.in[10];
;     const bf16_t* VN = (const bf16_t*)(a.ws + WS_E); bf16_t* GU = (bf16_t*)(a.ws + WS_D);
;     const float* STV = (const float*)(a.ws + WS_STAT); const float* lng = (const float*)a.in[7]; const float* lnb = (const float*)a.in[8];
;     LAS unsigned char* Wl = lds; LAS unsigned char* Vl = lds + 34816;
;     int gl = -1;
;     for (int it = blockIdx.x; it < 2048; it += G) {
;         const int g = it & 15, bc = it >> 4, r0 = (bc >> 4) * 2048 + (bc & 15) * 128, c0 = g * 128;
;         __syncthreads();
;         if (g != gl) { gl = g;
; #pragma unroll
;             for (int i = 0; i < 8; ++i) { const int idx4 = tid + 512 * i, q = idx4 >> 5, p4 = (idx4 & 31) * 4; f32x4 wv = *(const f32x4*)(Ws + (size_t)g * 16384 + q * 128 + p4);
; #pragma unroll
;                 for (int j = 0; j < 4; ++j) if (p4 + j > q) wv[j] = 0.f;
;                 u32x2 o; o.x = cvt_pk_bf16(wv[0], wv[1]); o.y = cvt_pk_bf16(wv[2], wv[3]); *(LAS u32x2*)(Wl + q * 272 + p4 * 2) = o; } }
; #pragma unroll
;         for (int i = 0; i < 4; ++i) { const int id = tid + 512 * i, p = id >> 4, dc = id & 15; const u32x4 vr = *(const u32x4*)(VN + (size_t)(r0 + p) * 2048 + c0 + dc * 8);
;             const float mean = STV[2 * (r0 + p)] * (1.0f / 2048.0f), rstd = 1.0f / sqrtf(fmaxf(STV[2 * (r0 + p) + 1] * (1.0f / 2048.0f) - mean * mean, 0.f) + EPS_);
;             const f32x4 g0 = *(const f32x4*)(lng + c0 + dc * 8), g1 = *(const f32x4*)(lng + c0 + dc * 8 + 4), b0 = *(const f32x4*)(lnb + c0 + dc * 8), b1 = *(const f32x4*)(lnb + c0 + dc * 8 + 4);
;             const f32x4 x0 = {bf_lo(vr.x), bf_hi(vr.x), bf_lo(vr.y), bf_hi(vr.y)}, x1 = {bf_lo(vr.z), bf_hi(vr.z), bf_lo(vr.w), bf_hi(vr.w)};
;             const u32x4 v = pack8((x0 - mean) * rstd * g0 + b0, (x1 - mean) * rstd * g1 + b1);
;             LAS unsigned short* vd = (LAS unsigned short*)(Vl + (dc * 8) * 272 + p * 2);
.LBB0_459:
	s_cmp_lt_i32 s82, 5
	s_cselect_b64 s[2:3], -1, 0
	s_cmp_gt_i32 s83, 4
	s_cselect_b64 s[4:5], -1, 0
	s_and_b64 s[80:81], s[2:3], s[4:5]
	s_andn2_b64 vcc, exec, s[80:81]
	s_cbranch_vccnz .LBB0_503
	s_waitcnt lgkmcnt(0)
	v_mbcnt_lo_u32_b32 v1, -1, 0
	v_mbcnt_hi_u32_b32 v1, -1, v1
	s_mov_b32 s77, s84
	v_or_b32_e32 v0, s90, v1
	s_cmpk_gt_i32 s33, 0x7ff
	v_readfirstlane_b32 s2, v0
	s_cbranch_scc1 .LBB0_468
	s_load_dwordx8 s[68:75], s[0:1], 0x38
	s_add_u32 s82, s78, 0x5300000
	v_lshlrev_b32_e32 v2, 2, v1
	s_addc_u32 s83, s79, 0
	v_and_b32_e32 v4, 0x7c, v2
	v_lshlrev_b32_e32 v2, 3, v1
	s_add_u32 s84, s78, 0x1eb00000
	v_lshlrev_b32_e32 v40, 2, v4
	v_mov_b32_e32 v41, 0
	v_and_b32_e32 v6, 0x78, v2
	s_addc_u32 s85, s79, 0
	s_waitcnt lgkmcnt(0)
	v_lshl_add_u64 v[42:43], s[72:73], 0, v[40:41]
	v_lshlrev_b32_e32 v40, 1, v6
	s_ashr_i32 s93, s2, 7
	v_lshl_add_u64 v[2:3], s[78:79], 0, v[40:41]
	v_lshlrev_b32_e32 v40, 2, v6
	s_cmp_gt_i32 s93, -1
	s_mov_b64 s[4:5], 0x9300000
	v_lshl_add_u64 v[46:47], s[68:69], 0, v[40:41]
	s_movk_i32 s68, 0x110
	s_cselect_b64 s[86:87], -1, 0
	s_ashr_i32 s69, s2, 2
	v_lshl_add_u64 v[44:45], v[2:3], 0, s[4:5]
	v_mad_u32_u24 v3, v6, s68, 0
	v_and_b32_e32 v109, -16, v6
	v_add_u32_e32 v3, v3, v109
	v_and_b32_e32 v6, 15, v1
	v_bfi_b32 v70, -16, s69, v1
	v_and_b32_e32 v7, 48, v1
	v_lshrrev_b32_e32 v1, 2, v1
	v_add_u32_e32 v10, 0x200, v0
	v_add_u32_e32 v12, 0x400, v0
	v_add_u32_e32 v14, 0x600, v0
	v_add_u32_e32 v16, 0x800, v0
	v_add_u32_e32 v17, 0xa00, v0
	v_add_u32_e32 v18, 0xc00, v0
	v_add_u32_e32 v19, 0xe00, v0
	v_and_b32_e32 v2, 12, v1
	v_ashrrev_i32_e32 v1, 5, v0
	v_or_b32_e32 v8, 2, v4
	v_or_b32_e32 v9, 3, v4
	v_ashrrev_i32_e32 v11, 5, v10
	v_ashrrev_i32_e32 v13, 5, v12
	v_ashrrev_i32_e32 v15, 5, v14
	v_ashrrev_i32_e32 v16, 5, v16
	v_ashrrev_i32_e32 v17, 5, v17
	v_ashrrev_i32_e32 v18, 5, v18
	v_ashrrev_i32_e32 v19, 5, v19
	v_lshl_add_u32 v5, v4, 1, 0
	v_lshlrev_b32_e32 v50, 7, v1
	v_cmp_gt_i32_e64 s[2:3], v4, v1
	v_cmp_lt_i32_e64 s[4:5], v4, v1
	v_cmp_gt_i32_e64 s[6:7], v8, v1
	v_cmp_gt_i32_e64 s[8:9], v9, v1
	v_mul_lo_u32 v1, v1, s68
	v_lshlrev_b32_e32 v52, 7, v11
	v_cmp_gt_i32_e64 s[10:11], v4, v11
	v_cmp_lt_i32_e64 s[12:13], v4, v11
	v_cmp_gt_i32_e64 s[14:15], v8, v11
	v_cmp_gt_i32_e64 s[16:17], v9, v11
	v_mul_lo_u32 v11, v11, s68
	v_lshlrev_b32_e32 v54, 7, v13
	v_cmp_gt_i32_e64 s[18:19], v4, v13
	v_cmp_lt_i32_e64 s[20:21], v4, v13
	v_cmp_gt_i32_e64 s[22:23], v8, v13
	v_cmp_gt_i32_e64 s[24:25], v9, v13
	v_mul_lo_u32 v13, v13, s68
	v_lshlrev_b32_e32 v56, 7, v15
	v_cmp_gt_i32_e64 s[26:27], v4, v15
	v_cmp_lt_i32_e64 s[28:29], v4, v15
	v_cmp_gt_i32_e64 s[30:31], v8, v15
	v_cmp_gt_i32_e64 s[34:35], v9, v15
	v_mul_lo_u32 v15, v15, s68
	v_lshlrev_b32_e32 v58, 7, v16
	v_cmp_gt_i32_e64 s[36:37], v4, v16
	v_cmp_lt_i32_e64 s[38:39], v4, v16
	v_cmp_gt_i32_e64 s[40:41], v8, v16
	v_cmp_gt_i32_e64 s[42:43], v9, v16
	v_mul_lo_u32 v16, v16, s68
	v_lshlrev_b32_e32 v60, 7, v17
	v_cmp_gt_i32_e64 s[44:45], v4, v17
	v_cmp_lt_i32_e64 s[46:47], v4, v17
	v_cmp_gt_i32_e64 s[48:49], v8, v17
	v_cmp_gt_i32_e64 s[50:51], v9, v17
	v_mul_lo_u32 v17, v17, s68
	v_lshlrev_b32_e32 v62, 7, v18
	v_cmp_gt_i32_e64 s[52:53], v4, v18
	v_cmp_lt_i32_e64 s[54:55], v4, v18
	v_cmp_gt_i32_e64 s[56:57], v8, v18
	v_cmp_gt_i32_e64 s[58:59], v9, v18
	v_mul_lo_u32 v18, v18, s68
	v_cmp_gt_i32_e64 s[60:61], v4, v19
	v_cmp_lt_i32_e64 s[62:63], v4, v19
	v_mul_lo_u32 v4, v19, s68
	v_ashrrev_i32_e32 v71, 4, v0
	v_ashrrev_i32_e32 v72, 4, v10
	v_ashrrev_i32_e32 v73, 4, v12
	v_ashrrev_i32_e32 v74, 4, v14
	v_mul_u32_u24_e32 v6, 0x110, v6
	s_lshr_b32 s68, s69, 4
	v_lshlrev_b32_e32 v64, 7, v19
	v_cmp_gt_i32_e64 s[64:65], v8, v19
	v_cmp_gt_i32_e64 s[66:67], v9, v19
	v_lshlrev_b32_e32 v0, 1, v71
	v_lshlrev_b32_e32 v8, 1, v72
	v_lshlrev_b32_e32 v9, 1, v73
	v_lshlrev_b32_e32 v10, 1, v74
	v_add3_u32 v6, v6, v7, 0
	s_mulk_i32 s68, 0x1100
	s_mov_b32 s73, 0
	v_lshl_add_u64 v[48:49], s[70:71], 0, v[40:41]
	s_mov_b32 s92, -1
	v_ashrrev_i32_e32 v51, 31, v50
	v_ashrrev_i32_e32 v53, 31, v52
	v_ashrrev_i32_e32 v55, 31, v54
	v_ashrrev_i32_e32 v57, 31, v56
	v_ashrrev_i32_e32 v59, 31, v58
	v_ashrrev_i32_e32 v61, 31, v60
	v_ashrrev_i32_e32 v63, 31, v62
	v_ashrrev_i32_e32 v65, 31, v64
	s_add_i32 s93, s93, 1
	v_add_u32_e32 v75, 0x8800, v6
	v_add_u32_e32 v76, s68, v6
	v_add_u32_e32 v77, v5, v1
	v_add_u32_e32 v78, v5, v11
	v_add_u32_e32 v79, v5, v13
	v_add_u32_e32 v80, v5, v15
	v_add_u32_e32 v81, v5, v16
	v_add_u32_e32 v82, v5, v17
	v_add_u32_e32 v83, v5, v18
	v_add_u32_e32 v84, v5, v4
	s_mov_b32 s88, 0x3a000000
	s_mov_b32 s94, 0xf800000
	v_mov_b32_e32 v85, 0x260
	v_add_u32_e32 v86, v3, v0
	v_add_u32_e32 v87, v3, v8
	v_add_u32_e32 v88, v3, v9
	v_add_u32_e32 v89, v3, v10
	v_lshlrev_b32_e32 v40, 1, v2
	s_mov_b32 s95, 0x5300000
	s_mov_b32 s96, s33
	s_branch .LBB0_463

; #define LAS __attribute__((address_space(3)))
; __device__ __forceinline__ void mix_phase(const Args& a, LAS unsigned char* lds, int G, int wv, size_t aa_out = WS_D) {
;     ...
;         for (int ks = 0; ks < nks; ++ks) {
;             const bf16x8 bw = *(const LAS bf16x8*)(Wl + (16 * w + (lane & 15)) * 272 + ks * 64 + (lane >> 4) * 16);
; #pragma unroll
;             for (int mb = 0; mb < 8; ++mb) { const bf16x8 av = *(const LAS bf16x8*)(Vl + (16 * mb + (lane & 15)) * 272 + ks * 64 + (lane >> 4) * 16);
;                 acc[mb] = __builtin_amdgcn_mfma_f32_16x16x32_bf16(av, bw, acc[mb], 0, 0, 0); }
;         }
.LBB0_467:
	ds_read_b128 v[34:37], v33
	ds_read_b128 v[66:69], v32
	ds_read_b128 v[90:93], v33 offset:4368
	s_add_i32 s68, s68, -1
	s_cmp_eq_u32 s68, 0
	v_add_u32_e32 v32, 64, v32
	s_waitcnt lgkmcnt(1)
	v_mfma_f32_16x16x32_bf16 v[28:31], v[34:37], v[66:69], v[28:31]
	ds_read_b128 v[34:37], v33 offset:8736
	s_waitcnt lgkmcnt(1)
	v_mfma_f32_16x16x32_bf16 v[24:27], v[90:93], v[66:69], v[24:27]
	ds_read_b128 v[90:93], v33 offset:13104
	s_waitcnt lgkmcnt(1)
	v_mfma_f32_16x16x32_bf16 v[20:23], v[34:37], v[66:69], v[20:23]
	ds_read_b128 v[34:37], v33 offset:17472
	s_waitcnt lgkmcnt(1)
	v_mfma_f32_16x16x32_bf16 v[16:19], v[90:93], v[66:69], v[16:19]
	ds_read_b128 v[90:93], v33 offset:21840
	s_waitcnt lgkmcnt(1)
	v_mfma_f32_16x16x32_bf16 v[12:15], v[34:37], v[66:69], v[12:15]
	ds_read_b128 v[34:37], v33 offset:26208
	s_waitcnt lgkmcnt(1)
	v_mfma_f32_16x16x32_bf16 v[8:11], v[90:93], v[66:69], v[8:11]
	ds_read_b128 v[90:93], v33 offset:30576
	v_add_u32_e32 v33, 64, v33
	s_waitcnt lgkmcnt(1)
	v_mfma_f32_16x16x32_bf16 v[4:7], v[34:37], v[66:69], v[4:7]
	s_waitcnt lgkmcnt(0)
	v_mfma_f32_16x16x32_bf16 v[0:3], v[90:93], v[66:69], v[0:3]
	s_cbranch_scc0 .LBB0_467
	s_branch .LBB0_462
